# v32 with the P2/P3 first/last split keyed on permuted-id bit 1
# baseline (speedup 1.0000x reference)
; #define LAS __attribute__((address_space(3)))
; DI float bf2f(unsigned short u) { return __uint_as_float(((unsigned)u) << 16); }
; DI float gamma_of(int h) { return 1.0f - exp2f(-5.0f - (float)h); }
; DI void ret_decode_unit(LAS unsigned char* lds, const bf16_t* Z, const float* S0, float* S1, bf16_t* MIX, const float* rng, int b, int h, int tid) {
;     LAS float* qv = (LAS float*)lds; LAS float* red = qv + 768;
;     const int lane = tid & 63, wid = tid >> 6;
;     const bf16_t* zrow = Z + (size_t)(LP + b) * INW;
;     if (tid < 256) { qv[tid] = bf2f(zrow[C_RQ + h * 256 + tid]); qv[256 + tid] = bf2f(zrow[C_RK + h * 256 + tid]); qv[512 + tid] = bf2f(zrow[C_RV + h * 256 + tid]); }
;     __syncthreads();
;     const float gm = gamma_of(h);
;     const f32x4 v4 = *(const LAS f32x4*)(qv + 512 + 4 * lane);
;     f32x4 acc = {0.f, 0.f, 0.f, 0.f};
;     const size_t off = ((size_t)(b * 4 + h) * 256 + wid * 32) * 256 + 4 * lane;
;     const float* s0 = S0 + off; float* s1 = S1 + off;
; __global__ void __launch_bounds__(512, 2) fwd_kernel(Args a) {
;     ...
;     if (IN(2)) for (int rep_ = 0; rep_ < 1 + ((DUPMASK >> 2) & 1); ++rep_) { if (rep_) xcd_barrier(bar);
;         if (bx & 1) for (int u = bx; u < 256; u += G) ret_decode_unit(lds, Z, state0, out + O_SS, MIX, rng, u >> 2, u & 3, tid);
;         for (int u = bx; u < 256; u += G) ret_step1(lds, Z, KV, u >> 2, u & 3, tid);
;         if (!(bx & 1)) for (int u = bx; u < 256; u += G) ret_decode_unit(lds, Z, state0, out + O_SS, MIX, rng, u >> 2, u & 3, tid);
;     }
.LBB0_226:
	s_and_b32 s98, s92, 7
	s_lshl_b32 s98, s98, 5
	s_lshr_b32 s99, s92, 3
	s_or_b32 s92, s98, s99
	s_cmp_lt_i32 s62, 3
	s_cselect_b64 s[2:3], -1, 0
	s_add_u32 s56, s60, 0x8000000
	s_addc_u32 s57, s61, 0
	s_add_u32 s4, s60, 0xfc00000
	s_addc_u32 s5, s61, 0
	v_writelane_b32 v254, s4, 23
	s_and_b64 s[10:11], s[2:3], s[0:1]
	s_andn2_b64 vcc, exec, s[10:11]
	v_writelane_b32 v254, s5, 24
	v_lshrrev_b32_e32 v252, 6, v253
	v_cmp_gt_u32_e64 s[0:1], 64, v253
	s_cbranch_vccnz .LBB0_250
	s_bitcmp0_b32 s92, 1
	v_readlane_b32 s68, v254, 7
	s_cselect_b64 s[14:15], -1, 0
	s_cmpk_gt_i32 s92, 0xff
	v_readlane_b32 s82, v254, 21
	v_lshlrev_b32_e32 v0, 2, v253
	s_cselect_b64 s[2:3], -1, 0
	v_readlane_b32 s83, v254, 22
	s_add_u32 s12, s82, 0x5220000
	v_and_b32_e32 v147, 0xfc, v0
	v_readlane_b32 s72, v254, 11
	v_readlane_b32 s73, v254, 12
	s_addc_u32 s13, s83, 0
	s_movk_i32 s4, 0x100
	v_add_u32_e32 v146, 0, v0
	v_lshlrev_b32_e32 v20, 2, v147
	v_mov_b32_e32 v21, 0
	v_lshl_add_u32 v149, v252, 7, 0
	v_mul_u32_u24_e32 v0, 0x380, v252
	s_or_b64 s[2:3], s[14:15], s[2:3]
	s_mov_b32 s17, 0
	v_add_u32_e32 v144, 0x900, v253
	v_add_u32_e32 v145, 0xd00, v253
	v_cmp_gt_u32_e64 s[6:7], s4, v253
	v_add_u32_e32 v148, 0, v20
	v_lshl_or_b32 v128, v252, 13, v147
	v_mov_b32_e32 v129, v21
	v_add3_u32 v150, v149, v0, v20
	v_lshl_add_u64 v[130:131], s[72:73], 0, v[20:21]
	s_and_b64 vcc, exec, s[2:3]
	v_readlane_b32 s69, v254, 8
	v_readlane_b32 s70, v254, 9
	v_readlane_b32 s71, v254, 10
	v_readlane_b32 s74, v254, 13
	v_readlane_b32 s75, v254, 14
	v_readlane_b32 s76, v254, 15
	v_readlane_b32 s77, v254, 16
	v_readlane_b32 s78, v254, 17
	v_readlane_b32 s79, v254, 18
	v_readlane_b32 s80, v254, 19
	v_readlane_b32 s81, v254, 20
	s_cbranch_vccnz .LBB0_236
	v_mbcnt_lo_u32_b32 v0, -1, 0
	v_mov_b32_e32 v30, 0x42800000
	v_mov_b32_e32 v31, 0x358637bd
	v_mbcnt_hi_u32_b32 v32, -1, v0
	s_mov_b32 s18, s92
	s_branch .LBB0_230

; #define LAS __attribute__((address_space(3)))
; DI float bf2f(unsigned short u) { return __uint_as_float(((unsigned)u) << 16); }
; DI void attn_decode_unit(LAS unsigned char* lds, const bf16_t* Z, const float* ck, const float* cv, bf16_t* MIX, const float* gq, const float* gk, const float* sinks, float* o_k, float* o_v, int b, int kh, int tid) {
;     LAS float* Kc = (LAS float*)lds; LAS float* Vc = Kc + 129 * 68; LAS float* qs = Vc + 129 * 64; LAS float* pw = qs + 512;
;     const int lane = tid & 63, wid = tid >> 6;
; #pragma unroll
;     for (int k = 0; k < 4; ++k) {
;         const int it = k * 512 + tid, w = it >> 4, c4 = (it & 15) * 4;
;         const size_t src = ((size_t)(b * 128 + w) * 2 + kh) * 64 + c4;
;         const f32x4 k4 = *(const f32x4*)(ck + src), v4 = *(const f32x4*)(cv + src);
;         *(LAS f32x4*)(Kc + w * 68 + c4) = k4; *(LAS f32x4*)(Vc + w * 64 + c4) = v4;
;         if (w >= 1) { const size_t dst = ((size_t)(b * 128 + w - 1) * 2 + kh) * 64 + c4; *(f32x4*)(o_k + dst) = k4; *(f32x4*)(o_v + dst) = v4; }
;     }
;     const bf16_t* zrow = Z + (size_t)(LP + b) * INW;
;     const size_t dnew = ((size_t)(b * 128 + 127) * 2 + kh) * 64 + lane;
;     if (wid == 0) { const float kx = bf2f(zrow[C_AK + kh * 64 + lane]); const float ss = wave_sum(kx * kx); const float kn = kx * rsqrtf(ss * (1.0f / 64.0f) + EPS) * gk[lane];
;         Kc[128 * 68 + lane] = kn; o_k[dnew] = kn; }
;     if (wid == 1) { const float vx = bf2f(zrow[C_AV + kh * 64 + lane]); Vc[128 * 64 + lane] = vx; o_v[dnew] = vx; }
;     const int hq = kh * 8 + wid;
;     { const float qx = bf2f(zrow[hq * 64 + lane]); const float ss = wave_sum(qx * qx); qs[wid * 64 + lane] = qx * rsqrtf(ss * (1.0f / 64.0f) + EPS) * gq[lane] * 0.125f; }
; __global__ void __launch_bounds__(512, 2) fwd_kernel(Args a) {
;     ...
;         if (bx & 1) for (int u = bx; u < 256; u += G) attn_decode_unit(lds, Z, cache_k, cache_v, MIX, gq, gk, sinks, out + O_KS, out + O_VS, u >> 1, u & 1, tid);
;         for (int u = 256 + bx; u < 512; u += G) ret_decode_unit(lds, Z, state0, out + O_SS, MIX, rng, u >> 2, u & 3, tid);
;         if (!(bx & 1)) for (int u = bx; u < 256; u += G) attn_decode_unit(lds, Z, cache_k, cache_v, MIX, gq, gk, sinks, out + O_KS, out + O_VS, u >> 1, u & 1, tid);
.LBB0_310:
	v_readlane_b32 s0, v254, 39
	v_readlane_b32 s1, v254, 40
	s_or_b64 exec, exec, s[0:1]
	v_readlane_b32 s92, v254, 37
	s_bitcmp0_b32 s92, 1
	v_readlane_b32 s68, v254, 7
	s_cselect_b64 s[18:19], -1, 0
	s_cmpk_gt_i32 s92, 0xff
	v_readlane_b32 s82, v254, 21
	s_cselect_b64 s[4:5], -1, 0
	v_readlane_b32 s83, v254, 22
	s_add_u32 s14, s82, 0x4220000
	s_addc_u32 s15, s83, 0
	s_add_u32 s16, s82, 0x4a20000
	v_add_u32_e32 v3, 0x200, v253
	s_addc_u32 s17, s83, 0
	v_lshlrev_b32_e32 v0, 2, v253
	v_lshrrev_b32_e32 v42, 4, v3
	v_add_u32_e32 v3, 0x600, v253
	v_lshlrev_b32_e32 v8, 2, v152
	s_add_i32 s6, 0, 0x10a10
	v_lshrrev_b32_e32 v44, 4, v3
	v_add_u32_e32 v3, 0, v8
	v_add_u32_e32 v47, s6, v0
	s_movk_i32 s6, 0x10c
	s_add_i32 s7, 0, 0x11210
	v_and_b32_e32 v40, 60, v0
	v_lshrrev_b32_e32 v41, 4, v253
	v_mad_u32_u24 v48, v152, s6, v3
	s_movk_i32 s6, 0x210
	v_mov_b32_e32 v4, s7
	v_readlane_b32 s69, v254, 8
	v_mov_b32_e32 v9, 0
	v_lshl_add_u32 v56, v40, 2, 0
	v_mul_u32_u24_e32 v1, 0x110, v41
	v_lshlrev_b32_e32 v2, 8, v41
	v_or_b32_e32 v43, 64, v41
	v_add_u32_e32 v46, 0x8910, v3
	v_mul_u32_u24_e32 v3, 0x210, v252
	v_mad_u32_u24 v50, v252, s6, v4
	s_or_b64 s[4:5], s[18:19], s[4:5]
	v_readlane_b32 s84, v254, 27
	v_readlane_b32 s86, v254, 29
	v_readlane_b32 s88, v254, 31
	v_readlane_b32 s90, v254, 35
	s_mov_b32 s21, 0
	v_mul_u32_u24_e32 v57, 0x110, v42
	v_lshlrev_b32_e32 v58, 8, v42
	v_lshlrev_b32_e32 v59, 8, v43
	v_mul_u32_u24_e32 v60, 0x110, v44
	v_lshlrev_b32_e32 v61, 8, v44
	v_cmp_gt_u32_e64 s[0:1], 64, v253
	v_lshl_add_u64 v[20:21], s[68:69], 0, v[8:9]
	v_add_u32_e32 v45, 0, v0
	v_cmp_eq_u32_e64 s[8:9], 1, v252
	v_lshl_add_u64 v[22:23], s[58:59], 0, v[8:9]
	v_mul_i32_i24_e32 v49, 0xfffffef4, v152
	v_add_u32_e32 v51, v50, v8
	v_cmp_eq_u32_e64 s[10:11], 0, v152
	v_and_b32_e32 v62, 0xfc, v0
	s_and_b64 vcc, exec, s[4:5]
	v_lshl_add_u32 v52, v252, 8, 0
	v_add_u32_e32 v53, 0, v3
	v_lshlrev_b32_e32 v24, 1, v152
	v_add_u32_e32 v54, v56, v1
	v_add_u32_e32 v55, v56, v2
	v_readlane_b32 s85, v254, 28
	v_readlane_b32 s87, v254, 30
	v_readlane_b32 s89, v254, 32
	v_readlane_b32 s91, v254, 36
	v_readlane_b32 s93, v254, 38
	v_readlane_b32 s70, v254, 9
	v_readlane_b32 s71, v254, 10
	v_readlane_b32 s72, v254, 11
	v_readlane_b32 s73, v254, 12
	v_readlane_b32 s74, v254, 13
	v_readlane_b32 s75, v254, 14
	v_readlane_b32 s76, v254, 15
	v_readlane_b32 s77, v254, 16
	v_readlane_b32 s78, v254, 17
	v_readlane_b32 s79, v254, 18
	v_readlane_b32 s80, v254, 19
	v_readlane_b32 s81, v254, 20
	s_cbranch_vccnz .LBB0_325
	v_mbcnt_lo_u32_b32 v0, -1, 0
	v_mbcnt_hi_u32_b32 v0, -1, v0
	v_and_b32_e32 v1, 64, v0
	v_add_u32_e32 v1, 64, v1
	v_xor_b32_e32 v2, 1, v0
	v_cmp_lt_i32_e32 vcc, v2, v1
	s_movk_i32 s22, 0xfe00
	s_mov_b32 s23, -1
	v_cndmask_b32_e32 v2, v0, v2, vcc
	v_lshlrev_b32_e32 v14, 2, v2
	v_xor_b32_e32 v2, 2, v0
	v_cmp_lt_i32_e32 vcc, v2, v1
	v_mov_b32_e32 v27, 0x358637bd
	s_mov_b32 s12, 0x800000
	v_cndmask_b32_e32 v2, v0, v2, vcc
	v_lshlrev_b32_e32 v15, 2, v2
	v_xor_b32_e32 v2, 4, v0
	v_cmp_lt_i32_e32 vcc, v2, v1
	s_mov_b32 s13, s92
	s_nop 0
	v_cndmask_b32_e32 v2, v0, v2, vcc
	v_lshlrev_b32_e32 v16, 2, v2
	v_xor_b32_e32 v2, 8, v0
	v_cmp_lt_i32_e32 vcc, v2, v1
	s_nop 1
	v_cndmask_b32_e32 v2, v0, v2, vcc
	v_lshlrev_b32_e32 v17, 2, v2
	v_xor_b32_e32 v2, 16, v0
	v_cmp_lt_i32_e32 vcc, v2, v1
	s_nop 1
	v_cndmask_b32_e32 v2, v0, v2, vcc
	v_lshlrev_b32_e32 v18, 2, v2
	v_xor_b32_e32 v2, 32, v0
	v_cmp_lt_i32_e32 vcc, v2, v1
	s_nop 1
	v_cndmask_b32_e32 v0, v0, v2, vcc
	v_lshlrev_b32_e32 v19, 2, v0
	v_add_u32_e32 v0, 0, v62
	v_add_u32_e32 v26, 0x8910, v0
